# code touch also at kernel entry (first 32 KB of instructions)
# baseline (speedup 1.0000x reference)
; #define LAS __attribute__((address_space(3)))
; __device__ __forceinline__ unsigned xb_add(unsigned* p, unsigned v) { return __hip_atomic_fetch_add(p, v, __ATOMIC_RELAXED, __HIP_MEMORY_SCOPE_AGENT); }
; __device__ __forceinline__ unsigned xb_xcc_id() { return (unsigned)__builtin_amdgcn_s_getreg((3 << 11) | 20) & 0xFu; }
; #define PF fresh_params()
; __device__ __forceinline__ XcdBarrier xcd_barrier_post(unsigned* bar, volatile LAS unsigned* st) {
;     XcdBarrier b; b.bar = bar; b.x = xb_xcc_id(); b.st = st;
;     if (threadIdx.x == 0) { st[2] = xb_add(&bar[XB_XCNT(b.x)], 1u); st[4] = b.x; }
;     return b;
; __global__ void __launch_bounds__(BLOCK_THREADS, 2) mega(Params p_unused) {
;     __shared__ __attribute__((aligned(16))) char lds[LDS_BYTES];
;     cg::grid_group grid = cg::this_grid();
;     volatile LAS unsigned* st = (volatile LAS unsigned*)(lds + 2 * LDS_MAIN);
;     if (threadIdx.x < 16) st[threadIdx.x] = 0u;
;     __syncthreads();
;     XcdBarrier xb = xcd_barrier_post((unsigned*)PF.ws, st);
_Z4mega6Params:
	s_load_dwordx2 s[76:77], s[0:1], 0xe0
	s_load_dword s84, s[0:1], 0xe8
	s_mov_b64 s[80:81], s[0:1]
	s_add_u32 s12, s80, 0xe0
	v_and_b32_e32 v158, 0x3ff, v0
	s_getpc_b64 s[98:99]
	v_lshlrev_b32_e32 v250, 4, v158
	v_mov_b32_e32 v251, 0
	v_lshl_add_u64 v[250:251], s[98:99], 0, v[250:251]
	v_and_b32_e32 v250, -16, v250
	global_load_dwordx4 v[252:255], v[250:251], off
	v_lshl_add_u64 v[250:251], 64, 7, v[250:251]
	global_load_dwordx4 v[252:255], v[250:251], off
	v_lshl_add_u64 v[250:251], 64, 7, v[250:251]
	global_load_dwordx4 v[252:255], v[250:251], off
	v_lshl_add_u64 v[250:251], 64, 7, v[250:251]
	global_load_dwordx4 v[252:255], v[250:251], off
	s_addc_u32 s13, s81, 0
	v_cmp_gt_u32_e32 vcc, 16, v158
	v_writelane_b32 v222, s2, 0
	s_and_saveexec_b64 s[4:5], vcc
	v_mov_b32_e32 v1, 0x24000
	v_lshl_or_b32 v1, v158, 2, v1
	v_mov_b32_e32 v2, 0
	ds_write_b32 v1, v2
	s_or_b64 exec, exec, s[4:5]
	s_mov_b64 s[0:1], s[80:81]
	s_waitcnt lgkmcnt(0)
	s_barrier
	s_load_dwordx2 s[78:79], s[0:1], 0xd8
	s_getreg_b32 s0, hwreg(HW_REG_XCC_ID, 0, 4)
	s_and_b32 s83, s0, 15
	v_cmp_eq_u32_e64 s[0:1], 0, v158
	s_mov_b64 s[4:5], exec
	s_nop 0
	v_writelane_b32 v222, s0, 1
	s_nop 1
	v_writelane_b32 v222, s1, 2
	s_and_b64 s[0:1], s[4:5], s[0:1]
	s_mov_b64 exec, s[0:1]
	s_cbranch_execz .LBB0_6
	s_mov_b64 s[8:9], exec
	v_mbcnt_lo_u32_b32 v1, s8, 0
	v_mbcnt_hi_u32_b32 v1, s9, v1
	v_cmp_eq_u32_e32 vcc, 0, v1
	s_and_saveexec_b64 s[6:7], vcc
	s_cbranch_execz .LBB0_5
	s_lshl_b32 s0, s83, 8
	s_bcnt1_i32_b64 s1, s[8:9]
	v_mov_b32_e32 v2, s0
	v_mov_b32_e32 v3, s1
	s_waitcnt lgkmcnt(0)
	global_atomic_add v2, v2, v3, s[78:79] offset:1024 sc0
